# residual-add GEMM epilogue: next row group base loads kept in flight (raw bf16 unpacked one group later, counted waits)
# baseline (speedup 1.0000x reference)
; DI float bf_lo(unsigned w) { return __uint_as_float(w << 16); }
; DI float bf_hi(unsigned w) { return __uint_as_float(w & 0xffff0000u); }
;   DI void operator()(const f32x4 (&acc)[2][2][4][2], const Unit& u, int wr, int wc, int fr, int fq) const {
;     const int row0 = u.pm * 256 + wr * 64 + fr, col0 = u.pn * 256 + wc * 32 + 4 * fq;
;     f32x4 cur[4], nxt[4];
;     auto loadrow = [&](int row, f32x4 (&d)[4]) {
;       const size_t off = (size_t)row * DM + col0;
;       if (basef) {
; #pragma unroll
;         for (int q = 0; q < 4; ++q) d[q] = *(const f32x4*)(basef + off + (q >> 1) * 128 + (q & 1) * 16);
;       } else {
; #pragma unroll
;         for (int q = 0; q < 4; ++q) { const u32x2 w = *(const u32x2*)(baseh + off + (q >> 1) * 128 + (q & 1) * 16); d[q] = (f32x4){bf_lo(w.x), bf_hi(w.x), bf_lo(w.y), bf_hi(w.y)}; }
;       }
;     };
;     loadrow(row0, cur);
.LBB0_332:
	v_lshl_add_u32 v176, s87, 8, v165
	v_lshl_or_b32 v178, s86, 8, v185
	v_ashrrev_i32_e32 v177, 31, v176
	v_lshlrev_b64 v[130:131], 11, v[176:177]
	v_ashrrev_i32_e32 v179, 31, v178
	v_cndmask_b32_e64 v132, 0, 1, s[50:51]
	v_cmp_ne_u32_e64 s[48:49], 1, v132
	s_nop 3
	s_mov_b64 s[98:99], s[48:49]
	s_andn2_b64 vcc, exec, s[50:51]
	v_lshl_add_u64 v[182:183], v[130:131], 0, v[178:179]
	s_cbranch_vccnz .LBB0_519
	v_lshl_add_u64 v[130:131], v[182:183], 2, s[68:69]
	global_load_dwordx4 v[158:161], v[130:131], off
	global_load_dwordx4 v[154:157], v[130:131], off offset:64
	global_load_dwordx4 v[150:153], v[130:131], off offset:512
	global_load_dwordx4 v[146:149], v[130:131], off offset:576
	s_cbranch_execnz .LBB0_335
.LBB0_334:
	v_lshl_add_u64 v[130:131], v[182:183], 1, s[6:7]
	global_load_dwordx2 v[216:217], v[130:131], off
	global_load_dwordx2 v[218:219], v[130:131], off offset:32
	global_load_dwordx2 v[220:221], v[130:131], off offset:256
	global_load_dwordx2 v[222:223], v[130:131], off offset:288

;   DI void operator()(const f32x4 (&acc)[2][2][4][2], const Unit& u, int wr, int wc, int fr, int fq) const {
;     ...
;     for (int idx = 0; idx < 8; ++idx) {
;       const int ai = idx >> 2, m = idx & 3;
;       const int row = row0 + ai * 128 + m * 16;
;       const size_t off = (size_t)row * DM + col0;
;       if (idx + 1 < 8) loadrow(row0 + ((idx + 1) >> 2) * 128 + ((idx + 1) & 3) * 16, nxt);
;       float ss = 0.f;
; #pragma unroll
;       for (int q = 0; q < 4; ++q) {
;         const int bj = q >> 1, n = q & 1;
;         const f32x4 o = cur[q] + acc[ai][bj][m][n];
;         if (out) *(f32x4*)(out + off + bj * 128 + n * 16) = o;
.LBB0_337:
	v_lshl_add_u64 v[130:131], v[180:181], 1, s[6:7]
	global_load_dwordx2 v[208:209], v[130:131], off
	global_load_dwordx2 v[210:211], v[130:131], off offset:32
	global_load_dwordx2 v[212:213], v[130:131], off offset:256
	global_load_dwordx2 v[214:215], v[130:131], off offset:288
.LBB0_338:
	s_and_b64 vcc, exec, s[98:99]
	s_cbranch_vccz .Lres_nc1
	s_waitcnt vmcnt(4)
	v_lshlrev_b32_e32 v158, 16, v216
	v_and_b32_e32 v159, 0xffff0000, v216
	v_lshlrev_b32_e32 v160, 16, v217
	v_and_b32_e32 v161, 0xffff0000, v217
	v_lshlrev_b32_e32 v154, 16, v218
	v_and_b32_e32 v155, 0xffff0000, v218
	v_lshlrev_b32_e32 v156, 16, v219
	v_and_b32_e32 v157, 0xffff0000, v219
	v_lshlrev_b32_e32 v150, 16, v220
	v_and_b32_e32 v151, 0xffff0000, v220
	v_lshlrev_b32_e32 v152, 16, v221
	v_and_b32_e32 v153, 0xffff0000, v221
	v_lshlrev_b32_e32 v146, 16, v222
	v_and_b32_e32 v147, 0xffff0000, v222
	v_lshlrev_b32_e32 v148, 16, v223
	v_and_b32_e32 v149, 0xffff0000, v223
.Lres_nc1:
	s_waitcnt vmcnt(4)
	v_pk_add_f32 v[126:127], v[126:127], v[158:159]
	v_cndmask_b32_e64 v158, 0, 1, s[54:55]
	v_pk_add_f32 v[128:129], v[128:129], v[160:161]
	v_cmp_ne_u32_e64 s[44:45], 1, v158
	s_andn2_b64 vcc, exec, s[54:55]
	v_lshl_add_u64 v[160:161], v[182:183], 2, s[64:65]
	s_cbranch_vccnz .LBB0_340
	global_store_dwordx4 v[160:161], v[126:129], off

;   DI void operator()(const f32x4 (&acc)[2][2][4][2], const Unit& u, int wr, int wc, int fr, int fq) const {
;     ...
;     for (int idx = 0; idx < 8; ++idx) {
;       const int ai = idx >> 2, m = idx & 3;
;       const int row = row0 + ai * 128 + m * 16;
;       const size_t off = (size_t)row * DM + col0;
;       if (idx + 1 < 8) loadrow(row0 + ((idx + 1) >> 2) * 128 + ((idx + 1) & 3) * 16, nxt);
;       float ss = 0.f;
; #pragma unroll
;       for (int q = 0; q < 4; ++q) {
;         const int bj = q >> 1, n = q & 1;
;         const f32x4 o = cur[q] + acc[ai][bj][m][n];
;         if (out) *(f32x4*)(out + off + bj * 128 + n * 16) = o;
.LBB0_360:
	v_lshl_add_u64 v[114:115], v[146:147], 1, s[6:7]
	global_load_dwordx2 v[216:217], v[114:115], off
	global_load_dwordx2 v[218:219], v[114:115], off offset:32
	global_load_dwordx2 v[220:221], v[114:115], off offset:256
	global_load_dwordx2 v[222:223], v[114:115], off offset:288
.LBB0_361:
	s_and_b64 vcc, exec, s[98:99]
	s_cbranch_vccz .Lres_nc2
	s_waitcnt vmcnt(4)
	v_lshlrev_b32_e32 v142, 16, v208
	v_and_b32_e32 v143, 0xffff0000, v208
	v_lshlrev_b32_e32 v144, 16, v209
	v_and_b32_e32 v145, 0xffff0000, v209
	v_lshlrev_b32_e32 v138, 16, v210
	v_and_b32_e32 v139, 0xffff0000, v210
	v_lshlrev_b32_e32 v140, 16, v211
	v_and_b32_e32 v141, 0xffff0000, v211
	v_lshlrev_b32_e32 v134, 16, v212
	v_and_b32_e32 v135, 0xffff0000, v212
	v_lshlrev_b32_e32 v136, 16, v213
	v_and_b32_e32 v137, 0xffff0000, v213
	v_lshlrev_b32_e32 v130, 16, v214
	v_and_b32_e32 v131, 0xffff0000, v214
	v_lshlrev_b32_e32 v132, 16, v215
	v_and_b32_e32 v133, 0xffff0000, v215
.Lres_nc2:
	s_waitcnt vmcnt(4)
	v_pk_add_f32 v[112:113], v[112:113], v[144:145]
	v_pk_add_f32 v[110:111], v[110:111], v[142:143]
	s_and_b64 vcc, exec, s[44:45]
	v_lshl_add_u64 v[144:145], v[180:181], 2, s[64:65]
	s_cbranch_vccnz .LBB0_363
	global_store_dwordx4 v[144:145], v[110:113], off

;   DI void operator()(const f32x4 (&acc)[2][2][4][2], const Unit& u, int wr, int wc, int fr, int fq) const {
;     ...
;     for (int idx = 0; idx < 8; ++idx) {
;       const int ai = idx >> 2, m = idx & 3;
;       const int row = row0 + ai * 128 + m * 16;
;       const size_t off = (size_t)row * DM + col0;
;       if (idx + 1 < 8) loadrow(row0 + ((idx + 1) >> 2) * 128 + ((idx + 1) & 3) * 16, nxt);
;       float ss = 0.f;
; #pragma unroll
;       for (int q = 0; q < 4; ++q) {
;         const int bj = q >> 1, n = q & 1;
;         const f32x4 o = cur[q] + acc[ai][bj][m][n];
;         if (out) *(f32x4*)(out + off + bj * 128 + n * 16) = o;
.LBB0_383:
	v_lshl_add_u64 v[98:99], v[130:131], 1, s[6:7]
	global_load_dwordx2 v[208:209], v[98:99], off
	global_load_dwordx2 v[210:211], v[98:99], off offset:32
	global_load_dwordx2 v[212:213], v[98:99], off offset:256
	global_load_dwordx2 v[214:215], v[98:99], off offset:288
.LBB0_384:
	s_and_b64 vcc, exec, s[98:99]
	s_cbranch_vccz .Lres_nc3
	s_waitcnt vmcnt(4)
	v_lshlrev_b32_e32 v126, 16, v216
	v_and_b32_e32 v127, 0xffff0000, v216
	v_lshlrev_b32_e32 v128, 16, v217
	v_and_b32_e32 v129, 0xffff0000, v217
	v_lshlrev_b32_e32 v122, 16, v218
	v_and_b32_e32 v123, 0xffff0000, v218
	v_lshlrev_b32_e32 v124, 16, v219
	v_and_b32_e32 v125, 0xffff0000, v219
	v_lshlrev_b32_e32 v118, 16, v220
	v_and_b32_e32 v119, 0xffff0000, v220
	v_lshlrev_b32_e32 v120, 16, v221
	v_and_b32_e32 v121, 0xffff0000, v221
	v_lshlrev_b32_e32 v114, 16, v222
	v_and_b32_e32 v115, 0xffff0000, v222
	v_lshlrev_b32_e32 v116, 16, v223
	v_and_b32_e32 v117, 0xffff0000, v223
.Lres_nc3:
	s_waitcnt vmcnt(4)
	v_pk_add_f32 v[96:97], v[96:97], v[128:129]
	v_pk_add_f32 v[94:95], v[94:95], v[126:127]
	s_and_b64 vcc, exec, s[44:45]
	v_lshl_add_u64 v[128:129], v[146:147], 2, s[64:65]
	s_cbranch_vccnz .LBB0_386
	global_store_dwordx4 v[128:129], v[94:97], off

;   DI void operator()(const f32x4 (&acc)[2][2][4][2], const Unit& u, int wr, int wc, int fr, int fq) const {
;     ...
;     for (int idx = 0; idx < 8; ++idx) {
;       const int ai = idx >> 2, m = idx & 3;
;       const int row = row0 + ai * 128 + m * 16;
;       const size_t off = (size_t)row * DM + col0;
;       if (idx + 1 < 8) loadrow(row0 + ((idx + 1) >> 2) * 128 + ((idx + 1) & 3) * 16, nxt);
;       float ss = 0.f;
; #pragma unroll
;       for (int q = 0; q < 4; ++q) {
;         const int bj = q >> 1, n = q & 1;
;         const f32x4 o = cur[q] + acc[ai][bj][m][n];
;         if (out) *(f32x4*)(out + off + bj * 128 + n * 16) = o;
.LBB0_406:
	v_lshl_add_u64 v[82:83], v[116:117], 1, s[6:7]
	global_load_dwordx2 v[216:217], v[82:83], off
	global_load_dwordx2 v[218:219], v[82:83], off offset:32
	global_load_dwordx2 v[220:221], v[82:83], off offset:256
	global_load_dwordx2 v[222:223], v[82:83], off offset:288
.LBB0_407:
	s_and_b64 vcc, exec, s[98:99]
	s_cbranch_vccz .Lres_nc4
	s_waitcnt vmcnt(4)
	v_lshlrev_b32_e32 v110, 16, v208
	v_and_b32_e32 v111, 0xffff0000, v208
	v_lshlrev_b32_e32 v112, 16, v209
	v_and_b32_e32 v113, 0xffff0000, v209
	v_lshlrev_b32_e32 v106, 16, v210
	v_and_b32_e32 v107, 0xffff0000, v210
	v_lshlrev_b32_e32 v108, 16, v211
	v_and_b32_e32 v109, 0xffff0000, v211
	v_lshlrev_b32_e32 v102, 16, v212
	v_and_b32_e32 v103, 0xffff0000, v212
	v_lshlrev_b32_e32 v104, 16, v213
	v_and_b32_e32 v105, 0xffff0000, v213
	v_lshlrev_b32_e32 v98, 16, v214
	v_and_b32_e32 v99, 0xffff0000, v214
	v_lshlrev_b32_e32 v100, 16, v215
	v_and_b32_e32 v101, 0xffff0000, v215
.Lres_nc4:
	s_waitcnt vmcnt(4)
	v_pk_add_f32 v[80:81], v[80:81], v[112:113]
	v_pk_add_f32 v[78:79], v[78:79], v[110:111]
	s_and_b64 vcc, exec, s[44:45]
	v_lshl_add_u64 v[112:113], v[130:131], 2, s[64:65]
	s_cbranch_vccnz .LBB0_409
	global_store_dwordx4 v[112:113], v[78:81], off

;   DI void operator()(const f32x4 (&acc)[2][2][4][2], const Unit& u, int wr, int wc, int fr, int fq) const {
;     ...
;     for (int idx = 0; idx < 8; ++idx) {
;       const int ai = idx >> 2, m = idx & 3;
;       const int row = row0 + ai * 128 + m * 16;
;       const size_t off = (size_t)row * DM + col0;
;       if (idx + 1 < 8) loadrow(row0 + ((idx + 1) >> 2) * 128 + ((idx + 1) & 3) * 16, nxt);
;       float ss = 0.f;
; #pragma unroll
;       for (int q = 0; q < 4; ++q) {
;         const int bj = q >> 1, n = q & 1;
;         const f32x4 o = cur[q] + acc[ai][bj][m][n];
;         if (out) *(f32x4*)(out + off + bj * 128 + n * 16) = o;
.LBB0_429:
	v_lshl_add_u64 v[66:67], v[98:99], 1, s[6:7]
	global_load_dwordx2 v[208:209], v[66:67], off
	global_load_dwordx2 v[210:211], v[66:67], off offset:32
	global_load_dwordx2 v[212:213], v[66:67], off offset:256
	global_load_dwordx2 v[214:215], v[66:67], off offset:288
.LBB0_430:
	s_and_b64 vcc, exec, s[98:99]
	s_cbranch_vccz .Lres_nc5
	s_waitcnt vmcnt(4)
	v_lshlrev_b32_e32 v94, 16, v216
	v_and_b32_e32 v95, 0xffff0000, v216
	v_lshlrev_b32_e32 v96, 16, v217
	v_and_b32_e32 v97, 0xffff0000, v217
	v_lshlrev_b32_e32 v90, 16, v218
	v_and_b32_e32 v91, 0xffff0000, v218
	v_lshlrev_b32_e32 v92, 16, v219
	v_and_b32_e32 v93, 0xffff0000, v219
	v_lshlrev_b32_e32 v86, 16, v220
	v_and_b32_e32 v87, 0xffff0000, v220
	v_lshlrev_b32_e32 v88, 16, v221
	v_and_b32_e32 v89, 0xffff0000, v221
	v_lshlrev_b32_e32 v82, 16, v222
	v_and_b32_e32 v83, 0xffff0000, v222
	v_lshlrev_b32_e32 v84, 16, v223
	v_and_b32_e32 v85, 0xffff0000, v223
.Lres_nc5:
	s_waitcnt vmcnt(4)
	v_pk_add_f32 v[64:65], v[64:65], v[96:97]
	v_pk_add_f32 v[62:63], v[62:63], v[94:95]
	s_and_b64 vcc, exec, s[44:45]
	v_lshl_add_u64 v[96:97], v[116:117], 2, s[64:65]
	s_cbranch_vccnz .LBB0_432
	global_store_dwordx4 v[96:97], v[62:65], off

;   DI void operator()(const f32x4 (&acc)[2][2][4][2], const Unit& u, int wr, int wc, int fr, int fq) const {
;     ...
;     for (int idx = 0; idx < 8; ++idx) {
;       const int ai = idx >> 2, m = idx & 3;
;       const int row = row0 + ai * 128 + m * 16;
;       const size_t off = (size_t)row * DM + col0;
;       if (idx + 1 < 8) loadrow(row0 + ((idx + 1) >> 2) * 128 + ((idx + 1) & 3) * 16, nxt);
;       float ss = 0.f;
; #pragma unroll
;       for (int q = 0; q < 4; ++q) {
;         const int bj = q >> 1, n = q & 1;
;         const f32x4 o = cur[q] + acc[ai][bj][m][n];
;         if (out) *(f32x4*)(out + off + bj * 128 + n * 16) = o;
.LBB0_452:
	v_lshl_add_u64 v[50:51], v[82:83], 1, s[6:7]
	global_load_dwordx2 v[216:217], v[50:51], off
	global_load_dwordx2 v[218:219], v[50:51], off offset:32
	global_load_dwordx2 v[220:221], v[50:51], off offset:256
	global_load_dwordx2 v[222:223], v[50:51], off offset:288
.LBB0_453:
	s_and_b64 vcc, exec, s[98:99]
	s_cbranch_vccz .Lres_nc6
	s_waitcnt vmcnt(4)
	v_lshlrev_b32_e32 v78, 16, v208
	v_and_b32_e32 v79, 0xffff0000, v208
	v_lshlrev_b32_e32 v80, 16, v209
	v_and_b32_e32 v81, 0xffff0000, v209
	v_lshlrev_b32_e32 v74, 16, v210
	v_and_b32_e32 v75, 0xffff0000, v210
	v_lshlrev_b32_e32 v76, 16, v211
	v_and_b32_e32 v77, 0xffff0000, v211
	v_lshlrev_b32_e32 v70, 16, v212
	v_and_b32_e32 v71, 0xffff0000, v212
	v_lshlrev_b32_e32 v72, 16, v213
	v_and_b32_e32 v73, 0xffff0000, v213
	v_lshlrev_b32_e32 v66, 16, v214
	v_and_b32_e32 v67, 0xffff0000, v214
	v_lshlrev_b32_e32 v68, 16, v215
	v_and_b32_e32 v69, 0xffff0000, v215
.Lres_nc6:
	s_waitcnt vmcnt(4)
	v_pk_add_f32 v[48:49], v[48:49], v[80:81]
	v_pk_add_f32 v[46:47], v[46:47], v[78:79]
	s_and_b64 vcc, exec, s[44:45]
	v_lshl_add_u64 v[80:81], v[98:99], 2, s[64:65]
	s_cbranch_vccnz .LBB0_455
	global_store_dwordx4 v[80:81], v[46:49], off

;   DI void operator()(const f32x4 (&acc)[2][2][4][2], const Unit& u, int wr, int wc, int fr, int fq) const {
;     ...
;     for (int idx = 0; idx < 8; ++idx) {
;       const int ai = idx >> 2, m = idx & 3;
;       const int row = row0 + ai * 128 + m * 16;
;       const size_t off = (size_t)row * DM + col0;
;       if (idx + 1 < 8) loadrow(row0 + ((idx + 1) >> 2) * 128 + ((idx + 1) & 3) * 16, nxt);
;       float ss = 0.f;
; #pragma unroll
;       for (int q = 0; q < 4; ++q) {
;         const int bj = q >> 1, n = q & 1;
;         const f32x4 o = cur[q] + acc[ai][bj][m][n];
;         if (out) *(f32x4*)(out + off + bj * 128 + n * 16) = o;
.LBB0_475:
	v_lshl_add_u64 v[34:35], v[66:67], 1, s[6:7]
	global_load_dwordx2 v[208:209], v[34:35], off
	global_load_dwordx2 v[210:211], v[34:35], off offset:32
	global_load_dwordx2 v[212:213], v[34:35], off offset:256
	global_load_dwordx2 v[214:215], v[34:35], off offset:288
.LBB0_476:
	s_and_b64 vcc, exec, s[98:99]
	s_cbranch_vccz .Lres_nc7
	s_waitcnt vmcnt(4)
	v_lshlrev_b32_e32 v62, 16, v216
	v_and_b32_e32 v63, 0xffff0000, v216
	v_lshlrev_b32_e32 v64, 16, v217
	v_and_b32_e32 v65, 0xffff0000, v217
	v_lshlrev_b32_e32 v58, 16, v218
	v_and_b32_e32 v59, 0xffff0000, v218
	v_lshlrev_b32_e32 v60, 16, v219
	v_and_b32_e32 v61, 0xffff0000, v219
	v_lshlrev_b32_e32 v54, 16, v220
	v_and_b32_e32 v55, 0xffff0000, v220
	v_lshlrev_b32_e32 v56, 16, v221
	v_and_b32_e32 v57, 0xffff0000, v221
	v_lshlrev_b32_e32 v50, 16, v222
	v_and_b32_e32 v51, 0xffff0000, v222
	v_lshlrev_b32_e32 v52, 16, v223
	v_and_b32_e32 v53, 0xffff0000, v223
.Lres_nc7:
	s_waitcnt vmcnt(4)
	v_pk_add_f32 v[32:33], v[32:33], v[64:65]
	v_pk_add_f32 v[30:31], v[30:31], v[62:63]
	s_and_b64 vcc, exec, s[44:45]
	v_lshl_add_u64 v[64:65], v[82:83], 2, s[64:65]
	s_cbranch_vccnz .LBB0_478
	global_store_dwordx4 v[64:65], v[30:33], off

; DI unsigned cvt_pk_bf16(float lo, float hi) { unsigned r; asm volatile("v_cvt_pk_bf16_f32 %0, %1, %2" : "=v"(r) : "v"(lo), "v"(hi)); return r; }
;   DI void operator()(const f32x4 (&acc)[2][2][4][2], const Unit& u, int wr, int wc, int fr, int fq) const {
;     ...
;     for (int idx = 0; idx < 8; ++idx) {
;       const int ai = idx >> 2, m = idx & 3;
;       const int row = row0 + ai * 128 + m * 16;
;       const size_t off = (size_t)row * DM + col0;
;       if (idx + 1 < 8) loadrow(row0 + ((idx + 1) >> 2) * 128 + ((idx + 1) & 3) * 16, nxt);
;       float ss = 0.f;
; #pragma unroll
;       for (int q = 0; q < 4; ++q) {
;         const int bj = q >> 1, n = q & 1;
;         const f32x4 o = cur[q] + acc[ai][bj][m][n];
;         if (out) *(f32x4*)(out + off + bj * 128 + n * 16) = o;
;         if (hb) { u32x2 w; w.x = cvt_pk_bf16(o[0], o[1]); w.y = cvt_pk_bf16(o[2], o[3]); *(u32x2*)(hb + off + bj * 128 + n * 16) = w; }
;         if (ssq) ss += o[0] * o[0] + o[1] * o[1] + o[2] * o[2] + o[3] * o[3];
;       }
;       if (ssq) { ss += __shfl_xor(ss, 16); ss += __shfl_xor(ss, 32); if (fq == 0) atomicAdd(ssq + row, (u64_t)(ss * 1048576.f)); }
; #pragma unroll
;       for (int q = 0; q < 4; ++q) cur[q] = nxt[q];
;     }
.LBB0_496:
	s_and_b64 vcc, exec, s[98:99]
	s_cbranch_vccz .Lres_nc8
	s_waitcnt vmcnt(0)
	v_lshlrev_b32_e32 v46, 16, v208
	v_and_b32_e32 v47, 0xffff0000, v208
	v_lshlrev_b32_e32 v48, 16, v209
	v_and_b32_e32 v49, 0xffff0000, v209
	v_lshlrev_b32_e32 v42, 16, v210
	v_and_b32_e32 v43, 0xffff0000, v210
	v_lshlrev_b32_e32 v44, 16, v211
	v_and_b32_e32 v45, 0xffff0000, v211
	v_lshlrev_b32_e32 v38, 16, v212
	v_and_b32_e32 v39, 0xffff0000, v212
	v_lshlrev_b32_e32 v40, 16, v213
	v_and_b32_e32 v41, 0xffff0000, v213
	v_lshlrev_b32_e32 v34, 16, v214
	v_and_b32_e32 v35, 0xffff0000, v214
	v_lshlrev_b32_e32 v36, 16, v215
	v_and_b32_e32 v37, 0xffff0000, v215
.Lres_nc8:
	s_waitcnt vmcnt(0)
	v_pk_add_f32 v[16:17], v[16:17], v[48:49]
	v_pk_add_f32 v[14:15], v[14:15], v[46:47]
	s_and_b64 vcc, exec, s[44:45]
	v_lshl_add_u64 v[20:21], v[66:67], 2, s[64:65]
	s_cbranch_vccnz .LBB0_498
	global_store_dwordx4 v[20:21], v[14:17], off

; __global__ void __launch_bounds__(512, 2) fwd_kernel(Params Parg) {
;   extern __shared__ __attribute__((aligned(16))) unsigned char shm[];
	.amdhsa_kernel _Z10fwd_kernel6Params
		.amdhsa_group_segment_fixed_size 0
		.amdhsa_private_segment_fixed_size 0
		.amdhsa_kernarg_size 2064
		.amdhsa_user_sgpr_count 2
		.amdhsa_user_sgpr_dispatch_ptr 0
		.amdhsa_user_sgpr_queue_ptr 0
		.amdhsa_user_sgpr_kernarg_segment_ptr 1
		.amdhsa_user_sgpr_dispatch_id 0
		.amdhsa_user_sgpr_kernarg_preload_length 0
		.amdhsa_user_sgpr_kernarg_preload_offset 0
		.amdhsa_user_sgpr_private_segment_size 0
		.amdhsa_uses_dynamic_stack 0
		.amdhsa_enable_private_segment 0
		.amdhsa_system_sgpr_workgroup_id_x 1
		.amdhsa_system_sgpr_workgroup_id_y 0
		.amdhsa_system_sgpr_workgroup_id_z 0
		.amdhsa_system_sgpr_workgroup_info 0
		.amdhsa_system_vgpr_workitem_id 2
		.amdhsa_next_free_vgpr 252
		.amdhsa_next_free_sgpr 100
		.amdhsa_accum_offset 252
		.amdhsa_reserve_vcc 1
		.amdhsa_float_round_mode_32 0
		.amdhsa_float_round_mode_16_64 0
		.amdhsa_float_denorm_mode_32 3
		.amdhsa_float_denorm_mode_16_64 3
		.amdhsa_dx10_clamp 1
		.amdhsa_ieee_mode 1
		.amdhsa_fp16_overflow 0
		.amdhsa_tg_split 0
		.amdhsa_exception_fp_ieee_invalid_op 0
		.amdhsa_exception_fp_denorm_src 0
		.amdhsa_exception_fp_ieee_div_zero 0
		.amdhsa_exception_fp_ieee_overflow 0
		.amdhsa_exception_fp_ieee_underflow 0
		.amdhsa_exception_fp_ieee_inexact 0
		.amdhsa_exception_int_div_zero 0
	.end_amdhsa_kernel

; __global__ void __launch_bounds__(512, 2) fwd_kernel(Params Parg) {
;   extern __shared__ __attribute__((aligned(16))) unsigned char shm[];
amdhsa.kernels:
  - .agpr_count:     0
    .args:
      - .offset:         0
        .size:           1808
        .value_kind:     by_value
      - .offset:         1808
        .size:           4
        .value_kind:     hidden_block_count_x
      - .offset:         1812
        .size:           4
        .value_kind:     hidden_block_count_y
      - .offset:         1816
        .size:           4
        .value_kind:     hidden_block_count_z
      - .offset:         1820
        .size:           2
        .value_kind:     hidden_group_size_x
      - .offset:         1822
        .size:           2
        .value_kind:     hidden_group_size_y
      - .offset:         1824
        .size:           2
        .value_kind:     hidden_group_size_z
      - .offset:         1826
        .size:           2
        .value_kind:     hidden_remainder_x
      - .offset:         1828
        .size:           2
        .value_kind:     hidden_remainder_y
      - .offset:         1830
        .size:           2
        .value_kind:     hidden_remainder_z
      - .offset:         1848
        .size:           8
        .value_kind:     hidden_global_offset_x
      - .offset:         1856
        .size:           8
        .value_kind:     hidden_global_offset_y
      - .offset:         1864
        .size:           8
        .value_kind:     hidden_global_offset_z
      - .offset:         1872
        .size:           2
        .value_kind:     hidden_grid_dims
      - .offset:         1896
        .size:           8
        .value_kind:     hidden_multigrid_sync_arg
      - .offset:         1928
        .size:           4
        .value_kind:     hidden_dynamic_lds_size
    .group_segment_fixed_size: 0
    .kernarg_segment_align: 8
    .kernarg_segment_size: 2064
    .language:       OpenCL C
    .language_version:
      - 2
      - 0
    .max_flat_workgroup_size: 512
    .name:           _Z10fwd_kernel6Params
    .private_segment_fixed_size: 0
    .sgpr_count:     106
    .sgpr_spill_count: 142
    .symbol:         _Z10fwd_kernel6Params.kd
    .uniform_work_group_size: 1
    .uses_dynamic_stack: false
    .vgpr_count:     252
    .vgpr_spill_count: 0
    .wavefront_size: 64
